# latent attention items and latent GLA-scan items remapped so that workgroups sharing K/V (same batch, kv-head) or KT/QE (same b,h,dir) run inside one XCD (L2 sharing instead of 8 XCDs streaming the sa
# speedup vs baseline: 1.0214x; 1.0018x over previous
.LBB0_346:
	s_and_b64 vcc, exec, s[20:21]
	s_cbranch_vccz .LBB0_313
	s_and_b32 s101, s8, 7
	s_lshr_b32 s100, s8, 3
	s_and_b32 s99, s101, 1
	s_lshl_b32 s99, s99, 1
	s_and_b32 s98, s100, 1
	s_or_b32 s99, s99, s98
	s_lshl_b32 s99, s99, 2
	s_bfe_u32 s98, s100, 0x20001
	s_or_b32 s99, s99, s98
	s_lshl_b32 s99, s99, 3
	s_lshr_b32 s98, s100, 3
	s_or_b32 s99, s99, s98
	s_lshr_b32 s101, s101, 1
	s_lshl_b32 s101, s101, 7
	s_or_b32 s101, s101, s99
	s_ashr_i32 s9, s101, 7
	s_bfe_u32 s24, s101, 0x40003
	s_lshl_b32 s16, s9, 10
	s_ashr_i32 s22, s9, 31
	s_mul_i32 s21, s9, 0xc0000
	s_mul_hi_i32 s20, s9, 0xc0000
	s_add_u32 s21, s33, s21
	s_addc_u32 s23, s30, s20
	s_lshl_b32 s20, s101, 1
	s_and_b32 s25, s20, 0xc0
	s_lshl_b32 s20, s25, 1
	s_add_u32 s20, s21, s20
	s_addc_u32 s21, s23, 0
	s_lshl_b32 s9, s9, 8
	s_or_b32 s9, s9, s25
	s_mul_hi_u32 s23, s9, 0xc00
	s_mulk_i32 s22, 0xc00
	s_add_i32 s23, s23, s22
	s_mulk_i32 s9, 0xc00
	s_add_u32 s22, s31, s9
	s_addc_u32 s23, s34, s23
	s_lshl_b32 s9, s101, 7
	s_and_b32 s9, s9, 0x380
	s_or_b32 s9, s16, s9
	v_add_u32_e32 v114, s9, v150
	v_ashrrev_i32_e32 v115, 31, v114
	v_lshlrev_b64 v[2:3], 11, v[114:115]
	v_mov_b32_e32 v107, v67
	v_lshl_add_u64 v[2:3], s[14:15], 0, v[2:3]
	s_lshl_b32 s16, s24, 7
	v_lshl_add_u64 v[4:5], s[22:23], 0, v[106:107]
	v_mov_b32_e32 v109, v67
	v_lshl_add_u64 v[2:3], v[2:3], 0, s[16:17]
	v_lshl_add_u64 v[118:119], v[4:5], 0, v[108:109]
	v_lshlrev_b32_e32 v66, 1, v68
	v_lshl_add_u64 v[116:117], s[20:21], 0, v[106:107]
	v_add_co_u32_e32 v10, vcc, s96, v118
	v_lshl_add_u64 v[2:3], v[2:3], 0, v[66:67]
	v_mov_b32_e32 v105, v67
	v_lshl_add_u64 v[18:19], v[116:117], 0, v[70:71]
	v_lshl_add_u64 v[4:5], v[116:117], 0, v[72:73]
	v_addc_co_u32_e32 v11, vcc, 0, v119, vcc
	v_lshl_add_u64 v[2:3], v[2:3], 0, v[104:105]
	s_mov_b32 s9, 0x8000
	global_load_dwordx4 v[6:9], v[4:5], off
	s_nop 0
	global_load_dwordx4 v[10:13], v[10:11], off
	s_nop 0
	global_load_dwordx4 v[14:17], v[118:119], off
	s_nop 0
	global_load_dwordx4 v[18:21], v[18:19], off
	v_add_co_u32_e32 v4, vcc, s9, v2
	v_mov_b32_e32 v111, v67
	s_nop 0
	v_addc_co_u32_e32 v5, vcc, 0, v3, vcc
	global_load_dwordx4 v[34:37], v[2:3], off
	global_load_dwordx4 v[38:41], v[4:5], off offset:64
	global_load_dwordx4 v[42:45], v[2:3], off offset:64
	global_load_dwordx4 v[46:49], v[4:5], off
	v_lshl_add_u64 v[2:3], v[116:117], 0, v[110:111]
	v_add_co_u32_e32 v4, vcc, s9, v2
	s_mov_b32 s9, 0xc000
	s_nop 0
	v_addc_co_u32_e32 v5, vcc, 0, v3, vcc
	v_lshl_add_u64 v[22:23], s[22:23], 0, v[108:109]
	v_add_co_u32_e32 v2, vcc, s9, v2
	v_lshl_add_u64 v[22:23], v[22:23], 0, v[106:107]
	s_nop 0
	v_addc_co_u32_e32 v3, vcc, 0, v3, vcc
	s_barrier
	global_load_dwordx4 v[50:53], v[4:5], off
	global_load_dwordx4 v[54:57], v[22:23], off offset:128
	v_add_co_u32_e32 v4, vcc, s96, v22
	v_xor_b32_e32 v22, 16, v156
	s_nop 0
	v_addc_co_u32_e32 v5, vcc, 0, v23, vcc
	global_load_dwordx4 v[58:61], v[2:3], off
	global_load_dwordx4 v[62:65], v[4:5], off offset:128
	v_and_b32_e32 v3, 64, v156
	v_add_u32_e32 v24, 64, v3
	v_xor_b32_e32 v23, 32, v156
	v_cmp_lt_i32_e32 vcc, v22, v24
	v_mov_b32_e32 v2, 0
	s_mov_b32 s21, 0
	v_cndmask_b32_e32 v22, v156, v22, vcc
	v_cmp_lt_i32_e32 vcc, v23, v24
	v_mov_b32_e32 v95, 0xf149f2ca
	v_mov_b32_e32 v3, v2
	v_cndmask_b32_e32 v23, v156, v23, vcc
	v_mov_b32_e32 v4, v2
	v_mov_b32_e32 v5, v2
	v_lshlrev_b32_e32 v89, 2, v22
	v_lshlrev_b32_e32 v87, 2, v23
	s_lshl_b32 s9, s24, 6
	v_mov_b32_e32 v26, v2
	v_mov_b32_e32 v27, v2
	v_mov_b32_e32 v28, v2
	v_mov_b32_e32 v29, v2
	v_mov_b32_e32 v22, v2
	s_waitcnt vmcnt(11)
	ds_write_b128 v142, v[6:9] offset:4608
	s_waitcnt vmcnt(10)
	ds_write_b128 v142, v[10:13] offset:13824
	s_waitcnt vmcnt(9)
	ds_write_b128 v142, v[14:17] offset:9216
	s_waitcnt vmcnt(8)
	ds_write_b128 v142, v[18:21]
	v_mov_b32_e32 v18, v2
	v_mov_b32_e32 v19, v2
	v_mov_b32_e32 v20, v2
	v_mov_b32_e32 v21, v2
	v_mov_b32_e32 v6, v2
	v_mov_b32_e32 v7, v2
	v_mov_b32_e32 v8, v2
	v_mov_b32_e32 v9, v2
	v_mov_b32_e32 v23, v2
	v_mov_b32_e32 v24, v2
	v_mov_b32_e32 v25, v2
	v_mov_b32_e32 v10, v2
	v_mov_b32_e32 v11, v2
	v_mov_b32_e32 v12, v2
	v_mov_b32_e32 v13, v2
	v_mov_b32_e32 v30, v2
	v_mov_b32_e32 v31, v2
	v_mov_b32_e32 v32, v2
	v_mov_b32_e32 v33, v2
	v_mov_b32_e32 v14, v2
	v_mov_b32_e32 v15, v2
	v_mov_b32_e32 v16, v2
	v_mov_b32_e32 v17, v2
	v_mov_b32_e32 v112, v2
	v_mov_b32_e32 v113, v2
	v_mov_b32_e32 v93, 0xf149f2ca
	s_waitcnt lgkmcnt(0)
	s_barrier

.LBB0_416:
	s_andn2_b64 vcc, exec, s[20:21]
	s_cbranch_vccnz .LBB0_418
	s_and_b32 s101, s24, 7
	s_bfe_u32 s100, s24, 0x40003
	s_lshr_b32 s99, s100, 2
	s_lshl_b32 s99, s99, 5
	s_lshr_b32 s98, s101, 1
	s_lshl_b32 s98, s98, 3
	s_or_b32 s99, s99, s98
	s_and_b32 s98, s101, 1
	s_lshl_b32 s98, s98, 2
	s_or_b32 s99, s99, s98
	s_and_b32 s98, s100, 3
	s_or_b32 s99, s99, s98
	s_andn2_b32 s101, s24, 0x7f
	s_or_b32 s101, s101, s99
	s_bfe_u32 s8, s101, 0x20005
	s_lshl_b32 s20, s8, 10
	s_or_b32 s26, s20, 0x2000
	s_ashr_i32 s20, s24, 5
	s_and_b32 s20, s20, -4
	s_sub_i32 s56, 12, s20
	s_mov_b32 s57, 15
	s_branch .LBB0_419
.LBB0_418:
	s_mov_b32 s101, s24
	s_mov_b32 s57, 3
	s_mov_b32 s56, 0
.LBB0_419:
	s_bfe_u32 s27, s101, 0x10002
	s_lshl_b32 s8, s8, 4
	s_lshl_b32 s20, s27, 2
	s_bfe_u32 s28, s101, 0x20003
	s_or_b32 s8, s8, s20
	s_or_b32 s8, s8, s28
	s_lshl_b64 s[20:21], s[8:9], 7
	s_lshl_b32 s8, s101, 6
	v_mov_b32_e32 v2, 0
	s_and_b32 s8, s8, 0xc0
	s_andn2_b64 vcc, exec, s[6:7]
	s_waitcnt vmcnt(11)
	v_or_b32_e32 v104, s20, v106
	v_or_b32_e32 v102, s20, v118
	s_waitcnt vmcnt(9)
	v_or_b32_e32 v100, s20, v120
	v_or_b32_e32 v98, s20, v122
	v_or_b32_e32 v96, s20, v124
	v_or_b32_e32 v94, s20, v126
	v_or_b32_e32 v92, s20, v128
	v_or_b32_e32 v90, s20, v130
	v_mov_b32_e32 v3, v2
	v_mov_b32_e32 v4, v2
	v_mov_b32_e32 v5, v2
	s_waitcnt vmcnt(6)
	v_mov_b32_e32 v6, v2
	v_mov_b32_e32 v7, v2
	v_mov_b32_e32 v8, v2
	v_mov_b32_e32 v9, v2
	s_waitcnt vmcnt(5)
	v_mov_b32_e32 v18, v2
	v_mov_b32_e32 v19, v2
	v_mov_b32_e32 v20, v2
	v_mov_b32_e32 v21, v2
	s_waitcnt vmcnt(4)
	v_mov_b32_e32 v10, v2
	v_mov_b32_e32 v11, v2
	v_mov_b32_e32 v12, v2
	v_mov_b32_e32 v13, v2
	s_waitcnt vmcnt(3)
	v_mov_b32_e32 v22, v2
	v_mov_b32_e32 v23, v2
	v_mov_b32_e32 v24, v2
	v_mov_b32_e32 v25, v2
	s_waitcnt vmcnt(2)
	v_mov_b32_e32 v14, v2
	v_mov_b32_e32 v15, v2
	v_mov_b32_e32 v16, v2
	v_mov_b32_e32 v17, v2
	s_waitcnt vmcnt(1)
	v_mov_b32_e32 v26, v2
	v_mov_b32_e32 v27, v2
	v_mov_b32_e32 v28, v2
	v_mov_b32_e32 v29, v2
	s_waitcnt vmcnt(0)
	v_mov_b32_e32 v30, v2
	v_mov_b32_e32 v31, v2
	v_mov_b32_e32 v32, v2
	v_mov_b32_e32 v33, v2
	s_cbranch_vccnz .LBB0_421
	s_lshl_b32 s6, s8, 2
	s_mov_b32 s7, s9
	v_mov_b32_e32 v105, s21
	v_mov_b32_e32 v103, s21
	v_mov_b32_e32 v101, s21
	v_mov_b32_e32 v99, s21
	v_mov_b32_e32 v97, s21
	v_mov_b32_e32 v95, s21
	v_mov_b32_e32 v93, s21
	v_mov_b32_e32 v91, s21
	v_lshl_add_u64 v[26:27], v[132:133], 0, s[6:7]
	v_lshlrev_b64 v[2:3], 10, v[104:105]
	v_lshlrev_b64 v[4:5], 10, v[102:103]
	v_lshlrev_b64 v[10:11], 10, v[100:101]
	v_lshlrev_b64 v[12:13], 10, v[98:99]
	v_lshlrev_b64 v[14:15], 10, v[96:97]
	v_lshlrev_b64 v[16:17], 10, v[94:95]
	v_lshlrev_b64 v[28:29], 10, v[92:93]
	v_lshlrev_b64 v[30:31], 10, v[90:91]
	v_lshl_add_u64 v[2:3], v[26:27], 0, v[2:3]
	v_lshl_add_u64 v[6:7], v[26:27], 0, v[4:5]
	v_lshl_add_u64 v[10:11], v[26:27], 0, v[10:11]
	v_lshl_add_u64 v[12:13], v[26:27], 0, v[12:13]
	v_lshl_add_u64 v[14:15], v[26:27], 0, v[14:15]
	v_lshl_add_u64 v[16:17], v[26:27], 0, v[16:17]
	v_lshl_add_u64 v[28:29], v[26:27], 0, v[28:29]
	v_lshl_add_u64 v[30:31], v[26:27], 0, v[30:31]
	global_load_dwordx4 v[2:5], v[2:3], off
	s_nop 0
	global_load_dwordx4 v[6:9], v[6:7], off
	s_nop 0
	global_load_dwordx4 v[18:21], v[10:11], off
	s_nop 0
	global_load_dwordx4 v[10:13], v[12:13], off
	s_nop 0
	global_load_dwordx4 v[22:25], v[14:15], off
	s_nop 0
	global_load_dwordx4 v[14:17], v[16:17], off
	s_nop 0
	global_load_dwordx4 v[26:29], v[28:29], off
	s_nop 0
	global_load_dwordx4 v[30:33], v[30:31], off

.LBB0_1086:
	s_and_b64 vcc, exec, s[10:11]
	s_cbranch_vccz .LBB0_1053
	s_and_b32 s101, s30, 7
	s_lshr_b32 s100, s30, 3
	s_and_b32 s99, s101, 1
	s_lshl_b32 s99, s99, 1
	s_and_b32 s98, s100, 1
	s_or_b32 s99, s99, s98
	s_lshl_b32 s99, s99, 2
	s_bfe_u32 s98, s100, 0x20001
	s_or_b32 s99, s99, s98
	s_lshl_b32 s99, s99, 3
	s_lshr_b32 s98, s100, 3
	s_or_b32 s99, s99, s98
	s_lshr_b32 s101, s101, 1
	s_lshl_b32 s101, s101, 7
	s_or_b32 s101, s101, s99
	s_ashr_i32 s10, s101, 7
	s_lshl_b32 s15, s10, 10
	s_add_i32 s10, s10, 4
	s_bfe_u32 s14, s101, 0x40003
	s_ashr_i32 s11, s10, 31
	s_mul_i32 s13, s10, 0xc0000
	s_mul_hi_i32 s12, s10, 0xc0000
	s_add_u32 s13, s33, s13
	s_addc_u32 s16, s20, s12
	s_lshl_b32 s12, s101, 1
	s_and_b32 s17, s12, 0xc0
	s_lshl_b32 s12, s17, 1
	s_add_u32 s12, s13, s12
	s_addc_u32 s13, s16, 0
	s_lshl_b64 s[10:11], s[10:11], 8
	s_or_b32 s10, s10, s17
	s_mulk_i32 s11, 0xc00
	s_mul_hi_u32 s16, s10, 0xc00
	s_add_i32 s16, s16, s11
	s_mulk_i32 s10, 0xc00
	s_add_u32 s10, s21, s10
	s_addc_u32 s11, s22, s16
	s_lshl_b32 s16, s101, 7
	s_and_b32 s16, s16, 0x380
	s_or_b32 s15, s15, s16
	v_add_u32_e32 v114, s15, v151
	v_ashrrev_i32_e32 v115, 31, v114
	v_lshlrev_b64 v[2:3], 11, v[114:115]
	v_mov_b32_e32 v107, v67
	v_lshl_add_u64 v[2:3], s[94:95], 0, v[2:3]
	s_lshl_b32 s96, s14, 7
	v_lshl_add_u64 v[4:5], s[10:11], 0, v[106:107]
	v_mov_b32_e32 v109, v67
	v_lshl_add_u64 v[2:3], v[2:3], 0, s[96:97]
	v_lshl_add_u64 v[118:119], v[4:5], 0, v[108:109]
	v_lshlrev_b32_e32 v66, 1, v68
	v_lshl_add_u64 v[116:117], s[12:13], 0, v[106:107]
	v_add_co_u32_e32 v10, vcc, s28, v118
	v_lshl_add_u64 v[2:3], v[2:3], 0, v[66:67]
	v_mov_b32_e32 v105, v67
	v_lshl_add_u64 v[18:19], v[116:117], 0, v[70:71]
	v_lshl_add_u64 v[4:5], v[116:117], 0, v[72:73]
	v_addc_co_u32_e32 v11, vcc, 0, v119, vcc
	v_lshl_add_u64 v[2:3], v[2:3], 0, v[104:105]
	s_mov_b32 s12, 0x8000
	global_load_dwordx4 v[6:9], v[4:5], off
	s_nop 0
	global_load_dwordx4 v[10:13], v[10:11], off
	s_nop 0
	global_load_dwordx4 v[14:17], v[118:119], off
	s_nop 0
	global_load_dwordx4 v[18:21], v[18:19], off
	v_add_co_u32_e32 v4, vcc, s12, v2
	v_mov_b32_e32 v111, v67
	s_nop 0
	v_addc_co_u32_e32 v5, vcc, 0, v3, vcc
	global_load_dwordx4 v[34:37], v[2:3], off
	global_load_dwordx4 v[38:41], v[4:5], off offset:64
	global_load_dwordx4 v[42:45], v[2:3], off offset:64
	global_load_dwordx4 v[46:49], v[4:5], off
	v_lshl_add_u64 v[2:3], v[116:117], 0, v[110:111]
	v_add_co_u32_e32 v4, vcc, s12, v2
	v_lshl_add_u64 v[22:23], s[10:11], 0, v[108:109]
	s_nop 0
	v_addc_co_u32_e32 v5, vcc, 0, v3, vcc
	s_mov_b32 s10, 0xc000
	v_add_co_u32_e32 v2, vcc, s10, v2
	v_lshl_add_u64 v[22:23], v[22:23], 0, v[106:107]
	s_nop 0
	v_addc_co_u32_e32 v3, vcc, 0, v3, vcc
	s_barrier
	global_load_dwordx4 v[50:53], v[4:5], off
	global_load_dwordx4 v[54:57], v[22:23], off offset:128
	v_add_co_u32_e32 v4, vcc, s28, v22
	v_xor_b32_e32 v22, 16, v157
	s_nop 0
	v_addc_co_u32_e32 v5, vcc, 0, v23, vcc
	global_load_dwordx4 v[58:61], v[2:3], off
	global_load_dwordx4 v[62:65], v[4:5], off offset:128
	v_and_b32_e32 v3, 64, v157
	v_add_u32_e32 v24, 64, v3
	v_xor_b32_e32 v23, 32, v157
	v_cmp_lt_i32_e32 vcc, v22, v24
	v_mov_b32_e32 v2, 0
	s_mov_b32 s12, 0
	v_cndmask_b32_e32 v22, v157, v22, vcc
	v_cmp_lt_i32_e32 vcc, v23, v24
	v_mov_b32_e32 v95, 0xf149f2ca
	v_mov_b32_e32 v3, v2
	v_cndmask_b32_e32 v23, v157, v23, vcc
	v_mov_b32_e32 v4, v2
	v_mov_b32_e32 v5, v2
	v_lshlrev_b32_e32 v89, 2, v22
	v_lshlrev_b32_e32 v87, 2, v23
	s_lshl_b32 s10, s14, 6
	v_mov_b32_e32 v26, v2
	v_mov_b32_e32 v27, v2
	v_mov_b32_e32 v28, v2
	v_mov_b32_e32 v29, v2
	v_mov_b32_e32 v22, v2
	s_waitcnt vmcnt(11)
	ds_write_b128 v143, v[6:9] offset:4608
	s_waitcnt vmcnt(10)
	ds_write_b128 v143, v[10:13] offset:13824
	s_waitcnt vmcnt(9)
	ds_write_b128 v143, v[14:17] offset:9216
	s_waitcnt vmcnt(8)
	ds_write_b128 v143, v[18:21]
	v_mov_b32_e32 v18, v2
	v_mov_b32_e32 v19, v2
	v_mov_b32_e32 v20, v2
	v_mov_b32_e32 v21, v2
	v_mov_b32_e32 v6, v2
	v_mov_b32_e32 v7, v2
	v_mov_b32_e32 v8, v2
	v_mov_b32_e32 v9, v2
	v_mov_b32_e32 v23, v2
	v_mov_b32_e32 v24, v2
	v_mov_b32_e32 v25, v2
	v_mov_b32_e32 v10, v2
	v_mov_b32_e32 v11, v2
	v_mov_b32_e32 v12, v2
	v_mov_b32_e32 v13, v2
	v_mov_b32_e32 v30, v2
	v_mov_b32_e32 v31, v2
	v_mov_b32_e32 v32, v2
	v_mov_b32_e32 v33, v2
	v_mov_b32_e32 v14, v2
	v_mov_b32_e32 v15, v2
	v_mov_b32_e32 v16, v2
	v_mov_b32_e32 v17, v2
	v_mov_b32_e32 v112, v2
	v_mov_b32_e32 v113, v2
	v_mov_b32_e32 v93, 0xf149f2ca
	s_waitcnt lgkmcnt(0)
	s_barrier

.LBB0_1156:
	s_andn2_b64 vcc, exec, s[20:21]
	s_cbranch_vccnz .LBB0_1158
	s_and_b32 s101, s24, 7
	s_bfe_u32 s100, s24, 0x40003
	s_lshr_b32 s99, s100, 2
	s_lshl_b32 s99, s99, 5
	s_lshr_b32 s98, s101, 1
	s_lshl_b32 s98, s98, 3
	s_or_b32 s99, s99, s98
	s_and_b32 s98, s101, 1
	s_lshl_b32 s98, s98, 2
	s_or_b32 s99, s99, s98
	s_and_b32 s98, s100, 3
	s_or_b32 s99, s99, s98
	s_andn2_b32 s101, s24, 0x7f
	s_or_b32 s101, s101, s99
	s_bfe_u32 s8, s101, 0x20005
	s_lshl_b32 s20, s8, 10
	s_or_b32 s26, s20, 0x2000
	s_ashr_i32 s20, s24, 5
	s_and_b32 s20, s20, -4
	s_sub_i32 s54, 12, s20
	s_mov_b32 s55, 15
	s_branch .LBB0_1159
.LBB0_1158:
	s_mov_b32 s101, s24
	s_mov_b32 s55, 3
	s_mov_b32 s54, 0
.LBB0_1159:
	s_bfe_u32 s27, s101, 0x10002
	s_lshl_b32 s8, s8, 4
	s_lshl_b32 s20, s27, 2
	s_bfe_u32 s28, s101, 0x20003
	s_or_b32 s8, s8, s20
	s_or_b32 s8, s8, s28
	s_or_b32 s8, s8, 8
	s_lshl_b64 s[20:21], s[8:9], 7
	s_lshl_b32 s8, s101, 6
	v_mov_b32_e32 v2, 0
	s_and_b32 s8, s8, 0xc0
	s_andn2_b64 vcc, exec, s[6:7]
	s_waitcnt vmcnt(11)
	v_or_b32_e32 v104, s20, v106
	v_or_b32_e32 v102, s20, v118
	s_waitcnt vmcnt(9)
	v_or_b32_e32 v100, s20, v120
	v_or_b32_e32 v98, s20, v122
	v_or_b32_e32 v96, s20, v124
	v_or_b32_e32 v94, s20, v126
	v_or_b32_e32 v92, s20, v128
	v_or_b32_e32 v90, s20, v132
	v_mov_b32_e32 v3, v2
	v_mov_b32_e32 v4, v2
	v_mov_b32_e32 v5, v2
	s_waitcnt vmcnt(6)
	v_mov_b32_e32 v6, v2
	v_mov_b32_e32 v7, v2
	v_mov_b32_e32 v8, v2
	v_mov_b32_e32 v9, v2
	s_waitcnt vmcnt(5)
	v_mov_b32_e32 v18, v2
	v_mov_b32_e32 v19, v2
	v_mov_b32_e32 v20, v2
	v_mov_b32_e32 v21, v2
	s_waitcnt vmcnt(4)
	v_mov_b32_e32 v10, v2
	v_mov_b32_e32 v11, v2
	v_mov_b32_e32 v12, v2
	v_mov_b32_e32 v13, v2
	s_waitcnt vmcnt(3)
	v_mov_b32_e32 v22, v2
	v_mov_b32_e32 v23, v2
	v_mov_b32_e32 v24, v2
	v_mov_b32_e32 v25, v2
	s_waitcnt vmcnt(2)
	v_mov_b32_e32 v14, v2
	v_mov_b32_e32 v15, v2
	v_mov_b32_e32 v16, v2
	v_mov_b32_e32 v17, v2
	s_waitcnt vmcnt(1)
	v_mov_b32_e32 v26, v2
	v_mov_b32_e32 v27, v2
	v_mov_b32_e32 v28, v2
	v_mov_b32_e32 v29, v2
	s_waitcnt vmcnt(0)
	v_mov_b32_e32 v30, v2
	v_mov_b32_e32 v31, v2
	v_mov_b32_e32 v32, v2
	v_mov_b32_e32 v33, v2
	s_cbranch_vccnz .LBB0_1161
	s_lshl_b32 s6, s8, 2
	s_mov_b32 s7, s9
	v_mov_b32_e32 v105, s21
	v_mov_b32_e32 v103, s21
	v_mov_b32_e32 v101, s21
	v_mov_b32_e32 v99, s21
	v_mov_b32_e32 v97, s21
	v_mov_b32_e32 v95, s21
	v_mov_b32_e32 v93, s21
	v_mov_b32_e32 v91, s21
	v_lshl_add_u64 v[26:27], v[134:135], 0, s[6:7]
	v_lshlrev_b64 v[2:3], 10, v[104:105]
	v_lshlrev_b64 v[4:5], 10, v[102:103]
	v_lshlrev_b64 v[10:11], 10, v[100:101]
	v_lshlrev_b64 v[12:13], 10, v[98:99]
	v_lshlrev_b64 v[14:15], 10, v[96:97]
	v_lshlrev_b64 v[16:17], 10, v[94:95]
	v_lshlrev_b64 v[28:29], 10, v[92:93]
	v_lshlrev_b64 v[30:31], 10, v[90:91]
	v_lshl_add_u64 v[2:3], v[26:27], 0, v[2:3]
	v_lshl_add_u64 v[6:7], v[26:27], 0, v[4:5]
	v_lshl_add_u64 v[10:11], v[26:27], 0, v[10:11]
	v_lshl_add_u64 v[12:13], v[26:27], 0, v[12:13]
	v_lshl_add_u64 v[14:15], v[26:27], 0, v[14:15]
	v_lshl_add_u64 v[16:17], v[26:27], 0, v[16:17]
	v_lshl_add_u64 v[28:29], v[26:27], 0, v[28:29]
	v_lshl_add_u64 v[30:31], v[26:27], 0, v[30:31]
	global_load_dwordx4 v[2:5], v[2:3], off
	s_nop 0
	global_load_dwordx4 v[6:9], v[6:7], off
	s_nop 0
	global_load_dwordx4 v[18:21], v[10:11], off
	s_nop 0
	global_load_dwordx4 v[10:13], v[12:13], off
	s_nop 0
	global_load_dwordx4 v[22:25], v[14:15], off
	s_nop 0
	global_load_dwordx4 v[14:17], v[16:17], off
	s_nop 0
	global_load_dwordx4 v[26:29], v[28:29], off
	s_nop 0
	global_load_dwordx4 v[30:33], v[30:31], off
